# hgrn pass 1 state-update step: decay and k' LDS reads issued ahead of the MFMAs with counted lgkmcnt (was 12 dependent LDS round trips)
# baseline (speedup 1.0000x reference)
.LBB0_331:
	v_mul_f32_e32 v69, v69, v40
	s_add_i32 s25, s5, s25
	v_lshlrev_b32_e32 v40, 1, v54
	s_waitcnt lgkmcnt(0)
	s_barrier
	v_add3_u32 v43, s25, v61, v40
	ds_read_u16 v96, v43
	ds_read_u16 v97, v43 offset:264
	ds_read_u16 v98, v43 offset:528
	ds_read_u16 v99, v43 offset:792
	ds_read_u16 v100, v43 offset:1056
	ds_read_u16 v101, v43 offset:1320
	ds_read_u16 v102, v43 offset:1584
	ds_read_u16 v103, v43 offset:1848
	v_add_u32_e32 v80, 0x18600, v62
	ds_read_b128 v[104:107], v80
	ds_read_b128 v[108:111], v80 offset:64
	ds_read_b128 v[112:115], v80 offset:128
	ds_read_b128 v[116:119], v80 offset:192
	ds_read_b128 v[120:123], v80 offset:256
	ds_read_b128 v[124:127], v80 offset:320
	ds_read_b128 v[128:131], v80 offset:384
	s_add_i32 s24, s24, 1
	v_subrev_u32_e32 v71, 32, v71
	v_add_u32_e32 v70, 32, v70
	s_cmp_eq_u32 s24, 16
	s_waitcnt lgkmcnt(7)
	v_lshl_or_b32 v40, v97, 16, v96
	v_lshl_or_b32 v41, v99, 16, v98
	v_lshl_or_b32 v42, v101, 16, v100
	v_lshl_or_b32 v43, v103, 16, v102
	ds_read_b128 v[132:135], v80 offset:448
	ds_read_b128 v[136:139], v66
	ds_read_b128 v[140:143], v66 offset:1280
	ds_read_b128 v[144:147], v66 offset:2560
	ds_read_b128 v[148:151], v67
	ds_read_b128 v[162:165], v66 offset:5120
	ds_read_b128 v[166:169], v66 offset:6400
	ds_read_b128 v[170:173], v66 offset:7680
	s_waitcnt lgkmcnt(6)
	v_pk_mul_f32 v[36:37], v[36:37], v[104:105]
	v_pk_mul_f32 v[38:39], v[38:39], v[106:107]
	ds_read_b128 v[174:177], v68
	s_nop 0
	v_mfma_f32_16x16x32_bf16 v[36:39], v[136:139], v[40:43], v[36:39]
	s_waitcnt lgkmcnt(6)
	v_pk_mul_f32 v[32:33], v[32:33], v[108:109]
	v_pk_mul_f32 v[34:35], v[34:35], v[110:111]
	s_nop 1
	v_mfma_f32_16x16x32_bf16 v[32:35], v[140:143], v[40:43], v[32:35]
	s_waitcnt lgkmcnt(5)
	v_pk_mul_f32 v[28:29], v[28:29], v[112:113]
	v_pk_mul_f32 v[30:31], v[30:31], v[114:115]
	s_nop 1
	v_mfma_f32_16x16x32_bf16 v[28:31], v[144:147], v[40:43], v[28:31]
	s_waitcnt lgkmcnt(4)
	v_pk_mul_f32 v[24:25], v[24:25], v[116:117]
	v_pk_mul_f32 v[26:27], v[26:27], v[118:119]
	s_nop 1
	v_mfma_f32_16x16x32_bf16 v[24:27], v[148:151], v[40:43], v[24:27]
	s_waitcnt lgkmcnt(3)
	v_pk_mul_f32 v[20:21], v[20:21], v[120:121]
	v_pk_mul_f32 v[22:23], v[22:23], v[122:123]
	s_nop 1
	v_mfma_f32_16x16x32_bf16 v[20:23], v[162:165], v[40:43], v[20:23]
	s_waitcnt lgkmcnt(2)
	v_pk_mul_f32 v[16:17], v[16:17], v[124:125]
	v_pk_mul_f32 v[18:19], v[18:19], v[126:127]
	s_nop 1
	v_mfma_f32_16x16x32_bf16 v[16:19], v[166:169], v[40:43], v[16:19]
	s_waitcnt lgkmcnt(1)
	v_pk_mul_f32 v[12:13], v[12:13], v[128:129]
	v_pk_mul_f32 v[14:15], v[14:15], v[130:131]
	s_nop 1
	v_mfma_f32_16x16x32_bf16 v[12:15], v[170:173], v[40:43], v[12:15]
	s_waitcnt lgkmcnt(0)
	v_pk_mul_f32 v[4:5], v[4:5], v[132:133]
	v_pk_mul_f32 v[6:7], v[6:7], v[134:135]
	s_nop 1
	v_mfma_f32_16x16x32_bf16 v[4:7], v[174:177], v[40:43], v[4:7]
	s_cbranch_scc1 .LBB0_336
